# adaLN group-finish (sum of 4 K-quarter partials + bias) loads batched 8 rows deep in P1/P4/P6, on top of residual-epilogue pipelining
# baseline (speedup 1.0000x reference)
; #define GAS __attribute__((address_space(1)))
; __device__ __forceinline__ void mod_group_finish(Frame& F, const Args& A, int chunk, int cg) {
;     ...
;     if (F.MISC[0] != 0u) {
;         const float* PART = (const float*)(A.ws + WS_PART); float* MOD = (float*)(A.ws + WS_MOD);
;         constexpr size_t PS = (size_t)(DBATCH + 1) * 12288;
; #pragma unroll 1
;         for (int i = threadIdx.x; i < (DBATCH + 1) * 64; i += NWAVES * 64) { const int r = i >> 6, c = 256 * cg + 4 * (i & 63);
;             const float* p = PART + (size_t)r * 12288 + c;
;             const f32x4 s = (*(const GAS f32x4*)p + *(const GAS f32x4*)(p + PS)) + (*(const GAS f32x4*)(p + 2 * PS) + *(const GAS f32x4*)(p + 3 * PS));
;             *(GAS f32x4*)(MOD + (size_t)r * MODW + 12288 * chunk + c) = s + *(const GAS f32x4*)(A.in[I_BADA] + 12288 * chunk + c); }
;     }
.LBB0_92:
	s_or_b64 exec, exec, s[16:17]
	v_mov_b32_e32 v2, s87
	s_waitcnt lgkmcnt(0)
	s_barrier
	ds_read_b32 v2, v2
	s_waitcnt lgkmcnt(0)
	v_cmp_eq_u32_e32 vcc, 0, v2
	s_cbranch_vccnz .LBB0_79
	s_add_u32 s36, s30, 0x63700000
	s_addc_u32 s37, s31, 0
	s_add_u32 s38, s36, 0x60c000
	s_addc_u32 s39, s37, 0
	s_add_u32 s40, s38, 0x60c000
	s_addc_u32 s41, s39, 0
	s_add_u32 s42, s40, 0x60c000
	s_addc_u32 s43, s41, 0
	s_add_u32 s44, s30, 0x38f00000
	s_addc_u32 s45, s31, 0
	v_lshrrev_b32_e32 v11, 6, v0
	v_or_b32_e32 v118, s14, v163
	v_lshlrev_b32_e32 v118, 2, v118
	v_mul_u32_u24_e32 v119, 0xc000, v11
	v_add_u32_e32 v119, v119, v118
	v_mul_u32_u24_e32 v120, 0x24000, v11
	v_add_u32_e32 v120, v120, v118
	global_load_dwordx4 v[114:117], v118, s[48:49]
	v_mov_b32_e32 v121, v119
	global_load_dwordx4 v[34:37], v121, s[36:37]
	global_load_dwordx4 v[38:41], v121, s[38:39]
	global_load_dwordx4 v[42:45], v121, s[40:41]
	global_load_dwordx4 v[46:49], v121, s[42:43]
	v_add_u32_e32 v121, 0x60000, v119
	global_load_dwordx4 v[50:53], v121, s[36:37]
	global_load_dwordx4 v[54:57], v121, s[38:39]
	global_load_dwordx4 v[58:61], v121, s[40:41]
	global_load_dwordx4 v[62:65], v121, s[42:43]
	v_add_u32_e32 v121, 0xc0000, v119
	global_load_dwordx4 v[66:69], v121, s[36:37]
	global_load_dwordx4 v[70:73], v121, s[38:39]
	global_load_dwordx4 v[74:77], v121, s[40:41]
	global_load_dwordx4 v[78:81], v121, s[42:43]
	v_add_u32_e32 v121, 0x120000, v119
	global_load_dwordx4 v[82:85], v121, s[36:37]
	global_load_dwordx4 v[86:89], v121, s[38:39]
	global_load_dwordx4 v[90:93], v121, s[40:41]
	global_load_dwordx4 v[94:97], v121, s[42:43]
	v_add_u32_e32 v121, 0x180000, v119
	global_load_dwordx4 v[98:101], v121, s[36:37]
	global_load_dwordx4 v[102:105], v121, s[38:39]
	global_load_dwordx4 v[106:109], v121, s[40:41]
	global_load_dwordx4 v[110:113], v121, s[42:43]
	v_add_u32_e32 v121, 0x1e0000, v119
	global_load_dwordx4 v[192:195], v121, s[36:37]
	global_load_dwordx4 v[196:199], v121, s[38:39]
	global_load_dwordx4 v[200:203], v121, s[40:41]
	global_load_dwordx4 v[204:207], v121, s[42:43]
	v_add_u32_e32 v121, 0x240000, v119
	global_load_dwordx4 v[208:211], v121, s[36:37]
	global_load_dwordx4 v[212:215], v121, s[38:39]
	global_load_dwordx4 v[216:219], v121, s[40:41]
	global_load_dwordx4 v[220:223], v121, s[42:43]
	v_add_u32_e32 v121, 0x2a0000, v119
	global_load_dwordx4 v[224:227], v121, s[36:37]
	global_load_dwordx4 v[228:231], v121, s[38:39]
	global_load_dwordx4 v[232:235], v121, s[40:41]
	global_load_dwordx4 v[236:239], v121, s[42:43]
	s_waitcnt vmcnt(28)
	v_pk_add_f32 v[36:37], v[36:37], v[40:41]
	v_pk_add_f32 v[34:35], v[34:35], v[38:39]
	v_pk_add_f32 v[38:39], v[44:45], v[48:49]
	v_pk_add_f32 v[40:41], v[42:43], v[46:47]
	v_pk_add_f32 v[36:37], v[36:37], v[38:39]
	v_pk_add_f32 v[34:35], v[34:35], v[40:41]
	v_pk_add_f32 v[36:37], v[116:117], v[36:37]
	v_pk_add_f32 v[34:35], v[114:115], v[34:35]
	v_mov_b32_e32 v121, v120
	global_store_dwordx4 v121, v[34:37], s[44:45]
	s_waitcnt vmcnt(25)
	v_pk_add_f32 v[52:53], v[52:53], v[56:57]
	v_pk_add_f32 v[50:51], v[50:51], v[54:55]
	v_pk_add_f32 v[54:55], v[60:61], v[64:65]
	v_pk_add_f32 v[56:57], v[58:59], v[62:63]
	v_pk_add_f32 v[52:53], v[52:53], v[54:55]
	v_pk_add_f32 v[50:51], v[50:51], v[56:57]
	v_pk_add_f32 v[52:53], v[116:117], v[52:53]
	v_pk_add_f32 v[50:51], v[114:115], v[50:51]
	v_add_u32_e32 v121, 0x120000, v120
	global_store_dwordx4 v121, v[50:53], s[44:45]
	s_waitcnt vmcnt(22)
	v_pk_add_f32 v[68:69], v[68:69], v[72:73]
	v_pk_add_f32 v[66:67], v[66:67], v[70:71]
	v_pk_add_f32 v[70:71], v[76:77], v[80:81]
	v_pk_add_f32 v[72:73], v[74:75], v[78:79]
	v_pk_add_f32 v[68:69], v[68:69], v[70:71]
	v_pk_add_f32 v[66:67], v[66:67], v[72:73]
	v_pk_add_f32 v[68:69], v[116:117], v[68:69]
	v_pk_add_f32 v[66:67], v[114:115], v[66:67]
	v_add_u32_e32 v121, 0x240000, v120
	global_store_dwordx4 v121, v[66:69], s[44:45]
	s_waitcnt vmcnt(19)
	v_pk_add_f32 v[84:85], v[84:85], v[88:89]
	v_pk_add_f32 v[82:83], v[82:83], v[86:87]
	v_pk_add_f32 v[86:87], v[92:93], v[96:97]
	v_pk_add_f32 v[88:89], v[90:91], v[94:95]
	v_pk_add_f32 v[84:85], v[84:85], v[86:87]
	v_pk_add_f32 v[82:83], v[82:83], v[88:89]
	v_pk_add_f32 v[84:85], v[116:117], v[84:85]
	v_pk_add_f32 v[82:83], v[114:115], v[82:83]
	v_add_u32_e32 v121, 0x360000, v120
	global_store_dwordx4 v121, v[82:85], s[44:45]
	s_waitcnt vmcnt(16)
	v_pk_add_f32 v[100:101], v[100:101], v[104:105]
	v_pk_add_f32 v[98:99], v[98:99], v[102:103]
	v_pk_add_f32 v[102:103], v[108:109], v[112:113]
	v_pk_add_f32 v[104:105], v[106:107], v[110:111]
	v_pk_add_f32 v[100:101], v[100:101], v[102:103]
	v_pk_add_f32 v[98:99], v[98:99], v[104:105]
	v_pk_add_f32 v[100:101], v[116:117], v[100:101]
	v_pk_add_f32 v[98:99], v[114:115], v[98:99]
	v_add_u32_e32 v121, 0x480000, v120
	global_store_dwordx4 v121, v[98:101], s[44:45]
	s_waitcnt vmcnt(13)
	v_pk_add_f32 v[194:195], v[194:195], v[198:199]
	v_pk_add_f32 v[192:193], v[192:193], v[196:197]
	v_pk_add_f32 v[196:197], v[202:203], v[206:207]
	v_pk_add_f32 v[198:199], v[200:201], v[204:205]
	v_pk_add_f32 v[194:195], v[194:195], v[196:197]
	v_pk_add_f32 v[192:193], v[192:193], v[198:199]
	v_pk_add_f32 v[194:195], v[116:117], v[194:195]
	v_pk_add_f32 v[192:193], v[114:115], v[192:193]
	v_add_u32_e32 v121, 0x5a0000, v120
	global_store_dwordx4 v121, v[192:195], s[44:45]
	s_waitcnt vmcnt(10)
	v_pk_add_f32 v[210:211], v[210:211], v[214:215]
	v_pk_add_f32 v[208:209], v[208:209], v[212:213]
	v_pk_add_f32 v[212:213], v[218:219], v[222:223]
	v_pk_add_f32 v[214:215], v[216:217], v[220:221]
	v_pk_add_f32 v[210:211], v[210:211], v[212:213]
	v_pk_add_f32 v[208:209], v[208:209], v[214:215]
	v_pk_add_f32 v[210:211], v[116:117], v[210:211]
	v_pk_add_f32 v[208:209], v[114:115], v[208:209]
	v_add_u32_e32 v121, 0x6c0000, v120
	global_store_dwordx4 v121, v[208:211], s[44:45]
	s_waitcnt vmcnt(7)
; #define GAS __attribute__((address_space(1)))
; __device__ __forceinline__ void mod_group_finish(Frame& F, const Args& A, int chunk, int cg) {
;     ...
;     if (F.MISC[0] != 0u) {
;         const float* PART = (const float*)(A.ws + WS_PART); float* MOD = (float*)(A.ws + WS_MOD);
;         constexpr size_t PS = (size_t)(DBATCH + 1) * 12288;
; #pragma unroll 1
;         for (int i = threadIdx.x; i < (DBATCH + 1) * 64; i += NWAVES * 64) { const int r = i >> 6, c = 256 * cg + 4 * (i & 63);
;             const float* p = PART + (size_t)r * 12288 + c;
;             const f32x4 s = (*(const GAS f32x4*)p + *(const GAS f32x4*)(p + PS)) + (*(const GAS f32x4*)(p + 2 * PS) + *(const GAS f32x4*)(p + 3 * PS));
;             *(GAS f32x4*)(MOD + (size_t)r * MODW + 12288 * chunk + c) = s + *(const GAS f32x4*)(A.in[I_BADA] + 12288 * chunk + c); }
;     }
	v_pk_add_f32 v[226:227], v[226:227], v[230:231]
	v_pk_add_f32 v[224:225], v[224:225], v[228:229]
	v_pk_add_f32 v[228:229], v[234:235], v[238:239]
	v_pk_add_f32 v[230:231], v[232:233], v[236:237]
	v_pk_add_f32 v[226:227], v[226:227], v[228:229]
	v_pk_add_f32 v[224:225], v[224:225], v[230:231]
	v_pk_add_f32 v[226:227], v[116:117], v[226:227]
	v_pk_add_f32 v[224:225], v[114:115], v[224:225]
	v_add_u32_e32 v121, 0x7e0000, v120
	global_store_dwordx4 v121, v[224:227], s[44:45]
	v_add_u32_e32 v121, 0x300000, v119
	global_load_dwordx4 v[34:37], v121, s[36:37]
	global_load_dwordx4 v[38:41], v121, s[38:39]
	global_load_dwordx4 v[42:45], v121, s[40:41]
	global_load_dwordx4 v[46:49], v121, s[42:43]
	v_add_u32_e32 v121, 0x360000, v119
	global_load_dwordx4 v[50:53], v121, s[36:37]
	global_load_dwordx4 v[54:57], v121, s[38:39]
	global_load_dwordx4 v[58:61], v121, s[40:41]
	global_load_dwordx4 v[62:65], v121, s[42:43]
	v_add_u32_e32 v121, 0x3c0000, v119
	global_load_dwordx4 v[66:69], v121, s[36:37]
	global_load_dwordx4 v[70:73], v121, s[38:39]
	global_load_dwordx4 v[74:77], v121, s[40:41]
	global_load_dwordx4 v[78:81], v121, s[42:43]
	v_add_u32_e32 v121, 0x420000, v119
	global_load_dwordx4 v[82:85], v121, s[36:37]
	global_load_dwordx4 v[86:89], v121, s[38:39]
	global_load_dwordx4 v[90:93], v121, s[40:41]
	global_load_dwordx4 v[94:97], v121, s[42:43]
	v_add_u32_e32 v121, 0x480000, v119
	global_load_dwordx4 v[98:101], v121, s[36:37]
	global_load_dwordx4 v[102:105], v121, s[38:39]
	global_load_dwordx4 v[106:109], v121, s[40:41]
	global_load_dwordx4 v[110:113], v121, s[42:43]
	v_add_u32_e32 v121, 0x4e0000, v119
	global_load_dwordx4 v[192:195], v121, s[36:37]
	global_load_dwordx4 v[196:199], v121, s[38:39]
	global_load_dwordx4 v[200:203], v121, s[40:41]
	global_load_dwordx4 v[204:207], v121, s[42:43]
	v_add_u32_e32 v121, 0x540000, v119
	global_load_dwordx4 v[208:211], v121, s[36:37]
	global_load_dwordx4 v[212:215], v121, s[38:39]
	global_load_dwordx4 v[216:219], v121, s[40:41]
	global_load_dwordx4 v[220:223], v121, s[42:43]
	v_add_u32_e32 v121, 0x5a0000, v119
	global_load_dwordx4 v[224:227], v121, s[36:37]
	global_load_dwordx4 v[228:231], v121, s[38:39]
	global_load_dwordx4 v[232:235], v121, s[40:41]
	global_load_dwordx4 v[236:239], v121, s[42:43]
	s_waitcnt vmcnt(28)
	v_pk_add_f32 v[36:37], v[36:37], v[40:41]
	v_pk_add_f32 v[34:35], v[34:35], v[38:39]
	v_pk_add_f32 v[38:39], v[44:45], v[48:49]
	v_pk_add_f32 v[40:41], v[42:43], v[46:47]
	v_pk_add_f32 v[36:37], v[36:37], v[38:39]
	v_pk_add_f32 v[34:35], v[34:35], v[40:41]
	v_pk_add_f32 v[36:37], v[116:117], v[36:37]
	v_pk_add_f32 v[34:35], v[114:115], v[34:35]
	v_add_u32_e32 v121, 0x900000, v120
	global_store_dwordx4 v121, v[34:37], s[44:45]
	s_waitcnt vmcnt(25)
	v_pk_add_f32 v[52:53], v[52:53], v[56:57]
	v_pk_add_f32 v[50:51], v[50:51], v[54:55]
	v_pk_add_f32 v[54:55], v[60:61], v[64:65]
	v_pk_add_f32 v[56:57], v[58:59], v[62:63]
	v_pk_add_f32 v[52:53], v[52:53], v[54:55]
	v_pk_add_f32 v[50:51], v[50:51], v[56:57]
	v_pk_add_f32 v[52:53], v[116:117], v[52:53]
	v_pk_add_f32 v[50:51], v[114:115], v[50:51]
	v_add_u32_e32 v121, 0xa20000, v120
	global_store_dwordx4 v121, v[50:53], s[44:45]
	s_waitcnt vmcnt(22)
	v_pk_add_f32 v[68:69], v[68:69], v[72:73]
	v_pk_add_f32 v[66:67], v[66:67], v[70:71]
	v_pk_add_f32 v[70:71], v[76:77], v[80:81]
	v_pk_add_f32 v[72:73], v[74:75], v[78:79]
	v_pk_add_f32 v[68:69], v[68:69], v[70:71]
	v_pk_add_f32 v[66:67], v[66:67], v[72:73]
	v_pk_add_f32 v[68:69], v[116:117], v[68:69]
	v_pk_add_f32 v[66:67], v[114:115], v[66:67]
	v_add_u32_e32 v121, 0xb40000, v120
	global_store_dwordx4 v121, v[66:69], s[44:45]
	s_waitcnt vmcnt(19)
	v_pk_add_f32 v[84:85], v[84:85], v[88:89]
	v_pk_add_f32 v[82:83], v[82:83], v[86:87]
	v_pk_add_f32 v[86:87], v[92:93], v[96:97]
	v_pk_add_f32 v[88:89], v[90:91], v[94:95]
	v_pk_add_f32 v[84:85], v[84:85], v[86:87]
	v_pk_add_f32 v[82:83], v[82:83], v[88:89]
	v_pk_add_f32 v[84:85], v[116:117], v[84:85]
	v_pk_add_f32 v[82:83], v[114:115], v[82:83]
	v_add_u32_e32 v121, 0xc60000, v120
	global_store_dwordx4 v121, v[82:85], s[44:45]
	s_waitcnt vmcnt(16)
	v_pk_add_f32 v[100:101], v[100:101], v[104:105]
	v_pk_add_f32 v[98:99], v[98:99], v[102:103]
	v_pk_add_f32 v[102:103], v[108:109], v[112:113]
	v_pk_add_f32 v[104:105], v[106:107], v[110:111]
	v_pk_add_f32 v[100:101], v[100:101], v[102:103]
	v_pk_add_f32 v[98:99], v[98:99], v[104:105]
	v_pk_add_f32 v[100:101], v[116:117], v[100:101]
	v_pk_add_f32 v[98:99], v[114:115], v[98:99]
	v_add_u32_e32 v121, 0xd80000, v120
	global_store_dwordx4 v121, v[98:101], s[44:45]
	s_waitcnt vmcnt(13)
	v_pk_add_f32 v[194:195], v[194:195], v[198:199]
	v_pk_add_f32 v[192:193], v[192:193], v[196:197]
	v_pk_add_f32 v[196:197], v[202:203], v[206:207]
	v_pk_add_f32 v[198:199], v[200:201], v[204:205]
	v_pk_add_f32 v[194:195], v[194:195], v[196:197]
	v_pk_add_f32 v[192:193], v[192:193], v[198:199]
	v_pk_add_f32 v[194:195], v[116:117], v[194:195]
	v_pk_add_f32 v[192:193], v[114:115], v[192:193]
	v_add_u32_e32 v121, 0xea0000, v120
	global_store_dwordx4 v121, v[192:195], s[44:45]
	s_waitcnt vmcnt(10)
	v_pk_add_f32 v[210:211], v[210:211], v[214:215]
	v_pk_add_f32 v[208:209], v[208:209], v[212:213]
	v_pk_add_f32 v[212:213], v[218:219], v[222:223]
	v_pk_add_f32 v[214:215], v[216:217], v[220:221]
	v_pk_add_f32 v[210:211], v[210:211], v[212:213]
	v_pk_add_f32 v[208:209], v[208:209], v[214:215]
	v_pk_add_f32 v[210:211], v[116:117], v[210:211]
	v_pk_add_f32 v[208:209], v[114:115], v[208:209]
	v_add_u32_e32 v121, 0xfc0000, v120
	global_store_dwordx4 v121, v[208:211], s[44:45]
	s_waitcnt vmcnt(7)
	v_pk_add_f32 v[226:227], v[226:227], v[230:231]
	v_pk_add_f32 v[224:225], v[224:225], v[228:229]
	v_pk_add_f32 v[228:229], v[234:235], v[238:239]
	v_pk_add_f32 v[230:231], v[232:233], v[236:237]
	v_pk_add_f32 v[226:227], v[226:227], v[228:229]
	v_pk_add_f32 v[224:225], v[224:225], v[230:231]
	v_pk_add_f32 v[226:227], v[116:117], v[226:227]
	v_pk_add_f32 v[224:225], v[114:115], v[224:225]
	v_add_u32_e32 v121, 0x10e0000, v120
	global_store_dwordx4 v121, v[224:227], s[44:45]
	v_cmp_gt_u32_e32 vcc, 64, v0
	s_and_saveexec_b64 s[16:17], vcc
	s_cbranch_execz .Lfs1_skip
	v_add_u32_e32 v121, 0x600000, v119
	global_load_dwordx4 v[34:37], v121, s[36:37]
	global_load_dwordx4 v[38:41], v121, s[38:39]
	global_load_dwordx4 v[42:45], v121, s[40:41]
	global_load_dwordx4 v[46:49], v121, s[42:43]
	s_waitcnt vmcnt(0)
	v_pk_add_f32 v[36:37], v[36:37], v[40:41]
	v_pk_add_f32 v[34:35], v[34:35], v[38:39]
	v_pk_add_f32 v[38:39], v[44:45], v[48:49]
	v_pk_add_f32 v[40:41], v[42:43], v[46:47]
	v_pk_add_f32 v[36:37], v[36:37], v[38:39]
	v_pk_add_f32 v[34:35], v[34:35], v[40:41]
	v_pk_add_f32 v[36:37], v[116:117], v[36:37]
	v_pk_add_f32 v[34:35], v[114:115], v[34:35]
	v_add_u32_e32 v121, 0x1200000, v120
	global_store_dwordx4 v121, v[34:37], s[44:45]
.Lfs1_skip:
	s_or_b64 exec, exec, s[16:17]
	s_branch .LBB0_79

; #define GAS __attribute__((address_space(1)))
; __device__ __forceinline__ void mod_group_finish(Frame& F, const Args& A, int chunk, int cg) {
;     ...
;     if (F.MISC[0] != 0u) {
;         const float* PART = (const float*)(A.ws + WS_PART); float* MOD = (float*)(A.ws + WS_MOD);
;         constexpr size_t PS = (size_t)(DBATCH + 1) * 12288;
; #pragma unroll 1
;         for (int i = threadIdx.x; i < (DBATCH + 1) * 64; i += NWAVES * 64) { const int r = i >> 6, c = 256 * cg + 4 * (i & 63);
;             const float* p = PART + (size_t)r * 12288 + c;
;             const f32x4 s = (*(const GAS f32x4*)p + *(const GAS f32x4*)(p + PS)) + (*(const GAS f32x4*)(p + 2 * PS) + *(const GAS f32x4*)(p + 3 * PS));
;             *(GAS f32x4*)(MOD + (size_t)r * MODW + 12288 * chunk + c) = s + *(const GAS f32x4*)(A.in[I_BADA] + 12288 * chunk + c); }
;     }
.LBB0_365:
	s_or_b64 exec, exec, s[16:17]
	v_mov_b32_e32 v2, s85
	s_waitcnt lgkmcnt(0)
	s_barrier
	ds_read_b32 v2, v2
	s_waitcnt lgkmcnt(0)
	v_cmp_eq_u32_e32 vcc, 0, v2
	s_cbranch_vccnz .LBB0_352
	s_add_u32 s36, s30, 0x63700000
	s_addc_u32 s37, s31, 0
	s_add_u32 s38, s36, 0x60c000
	s_addc_u32 s39, s37, 0
	s_add_u32 s40, s38, 0x60c000
	s_addc_u32 s41, s39, 0
	s_add_u32 s42, s40, 0x60c000
	s_addc_u32 s43, s41, 0
	s_add_u32 s44, s30, 0x38f0c000
	s_addc_u32 s45, s31, 0
	v_lshrrev_b32_e32 v11, 6, v0
	v_or_b32_e32 v118, s14, v161
	v_lshlrev_b32_e32 v118, 2, v118
	v_mul_u32_u24_e32 v119, 0xc000, v11
	v_add_u32_e32 v119, v119, v118
	v_mul_u32_u24_e32 v120, 0x24000, v11
	v_add_u32_e32 v120, v120, v118
	global_load_dwordx4 v[114:117], v118, s[6:7]
	v_mov_b32_e32 v121, v119
	global_load_dwordx4 v[34:37], v121, s[36:37]
	global_load_dwordx4 v[38:41], v121, s[38:39]
	global_load_dwordx4 v[42:45], v121, s[40:41]
	global_load_dwordx4 v[46:49], v121, s[42:43]
	v_add_u32_e32 v121, 0x60000, v119
	global_load_dwordx4 v[50:53], v121, s[36:37]
	global_load_dwordx4 v[54:57], v121, s[38:39]
	global_load_dwordx4 v[58:61], v121, s[40:41]
	global_load_dwordx4 v[62:65], v121, s[42:43]
	v_add_u32_e32 v121, 0xc0000, v119
	global_load_dwordx4 v[66:69], v121, s[36:37]
	global_load_dwordx4 v[70:73], v121, s[38:39]
	global_load_dwordx4 v[74:77], v121, s[40:41]
	global_load_dwordx4 v[78:81], v121, s[42:43]
	v_add_u32_e32 v121, 0x120000, v119
	global_load_dwordx4 v[82:85], v121, s[36:37]
	global_load_dwordx4 v[86:89], v121, s[38:39]
	global_load_dwordx4 v[90:93], v121, s[40:41]
	global_load_dwordx4 v[94:97], v121, s[42:43]
	v_add_u32_e32 v121, 0x180000, v119
	global_load_dwordx4 v[98:101], v121, s[36:37]
	global_load_dwordx4 v[102:105], v121, s[38:39]
	global_load_dwordx4 v[106:109], v121, s[40:41]
	global_load_dwordx4 v[110:113], v121, s[42:43]
	v_add_u32_e32 v121, 0x1e0000, v119
	global_load_dwordx4 v[192:195], v121, s[36:37]
	global_load_dwordx4 v[196:199], v121, s[38:39]
	global_load_dwordx4 v[200:203], v121, s[40:41]
	global_load_dwordx4 v[204:207], v121, s[42:43]
	v_add_u32_e32 v121, 0x240000, v119
	global_load_dwordx4 v[208:211], v121, s[36:37]
	global_load_dwordx4 v[212:215], v121, s[38:39]
	global_load_dwordx4 v[216:219], v121, s[40:41]
	global_load_dwordx4 v[220:223], v121, s[42:43]
	v_add_u32_e32 v121, 0x2a0000, v119
	global_load_dwordx4 v[224:227], v121, s[36:37]
	global_load_dwordx4 v[228:231], v121, s[38:39]
	global_load_dwordx4 v[232:235], v121, s[40:41]
	global_load_dwordx4 v[236:239], v121, s[42:43]
	s_waitcnt vmcnt(28)
	v_pk_add_f32 v[36:37], v[36:37], v[40:41]
	v_pk_add_f32 v[34:35], v[34:35], v[38:39]
	v_pk_add_f32 v[38:39], v[44:45], v[48:49]
	v_pk_add_f32 v[40:41], v[42:43], v[46:47]
	v_pk_add_f32 v[36:37], v[36:37], v[38:39]
	v_pk_add_f32 v[34:35], v[34:35], v[40:41]
	v_pk_add_f32 v[36:37], v[116:117], v[36:37]
	v_pk_add_f32 v[34:35], v[114:115], v[34:35]
	v_mov_b32_e32 v121, v120
	global_store_dwordx4 v121, v[34:37], s[44:45]
	s_waitcnt vmcnt(25)
	v_pk_add_f32 v[52:53], v[52:53], v[56:57]
	v_pk_add_f32 v[50:51], v[50:51], v[54:55]
	v_pk_add_f32 v[54:55], v[60:61], v[64:65]
	v_pk_add_f32 v[56:57], v[58:59], v[62:63]
	v_pk_add_f32 v[52:53], v[52:53], v[54:55]
	v_pk_add_f32 v[50:51], v[50:51], v[56:57]
	v_pk_add_f32 v[52:53], v[116:117], v[52:53]
	v_pk_add_f32 v[50:51], v[114:115], v[50:51]
	v_add_u32_e32 v121, 0x120000, v120
	global_store_dwordx4 v121, v[50:53], s[44:45]
	s_waitcnt vmcnt(22)
	v_pk_add_f32 v[68:69], v[68:69], v[72:73]
	v_pk_add_f32 v[66:67], v[66:67], v[70:71]
	v_pk_add_f32 v[70:71], v[76:77], v[80:81]
	v_pk_add_f32 v[72:73], v[74:75], v[78:79]
	v_pk_add_f32 v[68:69], v[68:69], v[70:71]
	v_pk_add_f32 v[66:67], v[66:67], v[72:73]
	v_pk_add_f32 v[68:69], v[116:117], v[68:69]
	v_pk_add_f32 v[66:67], v[114:115], v[66:67]
	v_add_u32_e32 v121, 0x240000, v120
	global_store_dwordx4 v121, v[66:69], s[44:45]
	s_waitcnt vmcnt(19)
	v_pk_add_f32 v[84:85], v[84:85], v[88:89]
	v_pk_add_f32 v[82:83], v[82:83], v[86:87]
	v_pk_add_f32 v[86:87], v[92:93], v[96:97]
	v_pk_add_f32 v[88:89], v[90:91], v[94:95]
	v_pk_add_f32 v[84:85], v[84:85], v[86:87]
	v_pk_add_f32 v[82:83], v[82:83], v[88:89]
	v_pk_add_f32 v[84:85], v[116:117], v[84:85]
	v_pk_add_f32 v[82:83], v[114:115], v[82:83]
	v_add_u32_e32 v121, 0x360000, v120
	global_store_dwordx4 v121, v[82:85], s[44:45]
	s_waitcnt vmcnt(16)
	v_pk_add_f32 v[100:101], v[100:101], v[104:105]
	v_pk_add_f32 v[98:99], v[98:99], v[102:103]
	v_pk_add_f32 v[102:103], v[108:109], v[112:113]
	v_pk_add_f32 v[104:105], v[106:107], v[110:111]
	v_pk_add_f32 v[100:101], v[100:101], v[102:103]
	v_pk_add_f32 v[98:99], v[98:99], v[104:105]
	v_pk_add_f32 v[100:101], v[116:117], v[100:101]
	v_pk_add_f32 v[98:99], v[114:115], v[98:99]
	v_add_u32_e32 v121, 0x480000, v120
	global_store_dwordx4 v121, v[98:101], s[44:45]
	s_waitcnt vmcnt(13)
	v_pk_add_f32 v[194:195], v[194:195], v[198:199]
	v_pk_add_f32 v[192:193], v[192:193], v[196:197]
	v_pk_add_f32 v[196:197], v[202:203], v[206:207]
	v_pk_add_f32 v[198:199], v[200:201], v[204:205]
	v_pk_add_f32 v[194:195], v[194:195], v[196:197]
	v_pk_add_f32 v[192:193], v[192:193], v[198:199]
	v_pk_add_f32 v[194:195], v[116:117], v[194:195]
	v_pk_add_f32 v[192:193], v[114:115], v[192:193]
	v_add_u32_e32 v121, 0x5a0000, v120
	global_store_dwordx4 v121, v[192:195], s[44:45]
	s_waitcnt vmcnt(10)
	v_pk_add_f32 v[210:211], v[210:211], v[214:215]
	v_pk_add_f32 v[208:209], v[208:209], v[212:213]
	v_pk_add_f32 v[212:213], v[218:219], v[222:223]
	v_pk_add_f32 v[214:215], v[216:217], v[220:221]
	v_pk_add_f32 v[210:211], v[210:211], v[212:213]
	v_pk_add_f32 v[208:209], v[208:209], v[214:215]
	v_pk_add_f32 v[210:211], v[116:117], v[210:211]
	v_pk_add_f32 v[208:209], v[114:115], v[208:209]
	v_add_u32_e32 v121, 0x6c0000, v120
	global_store_dwordx4 v121, v[208:211], s[44:45]
	s_waitcnt vmcnt(7)
; #define GAS __attribute__((address_space(1)))
; __device__ __forceinline__ void mod_group_finish(Frame& F, const Args& A, int chunk, int cg) {
;     ...
;     if (F.MISC[0] != 0u) {
;         const float* PART = (const float*)(A.ws + WS_PART); float* MOD = (float*)(A.ws + WS_MOD);
;         constexpr size_t PS = (size_t)(DBATCH + 1) * 12288;
; #pragma unroll 1
;         for (int i = threadIdx.x; i < (DBATCH + 1) * 64; i += NWAVES * 64) { const int r = i >> 6, c = 256 * cg + 4 * (i & 63);
;             const float* p = PART + (size_t)r * 12288 + c;
;             const f32x4 s = (*(const GAS f32x4*)p + *(const GAS f32x4*)(p + PS)) + (*(const GAS f32x4*)(p + 2 * PS) + *(const GAS f32x4*)(p + 3 * PS));
;             *(GAS f32x4*)(MOD + (size_t)r * MODW + 12288 * chunk + c) = s + *(const GAS f32x4*)(A.in[I_BADA] + 12288 * chunk + c); }
;     }
	v_pk_add_f32 v[226:227], v[226:227], v[230:231]
	v_pk_add_f32 v[224:225], v[224:225], v[228:229]
	v_pk_add_f32 v[228:229], v[234:235], v[238:239]
	v_pk_add_f32 v[230:231], v[232:233], v[236:237]
	v_pk_add_f32 v[226:227], v[226:227], v[228:229]
	v_pk_add_f32 v[224:225], v[224:225], v[230:231]
	v_pk_add_f32 v[226:227], v[116:117], v[226:227]
	v_pk_add_f32 v[224:225], v[114:115], v[224:225]
	v_add_u32_e32 v121, 0x7e0000, v120
	global_store_dwordx4 v121, v[224:227], s[44:45]
	v_add_u32_e32 v121, 0x300000, v119
	global_load_dwordx4 v[34:37], v121, s[36:37]
	global_load_dwordx4 v[38:41], v121, s[38:39]
	global_load_dwordx4 v[42:45], v121, s[40:41]
	global_load_dwordx4 v[46:49], v121, s[42:43]
	v_add_u32_e32 v121, 0x360000, v119
	global_load_dwordx4 v[50:53], v121, s[36:37]
	global_load_dwordx4 v[54:57], v121, s[38:39]
	global_load_dwordx4 v[58:61], v121, s[40:41]
	global_load_dwordx4 v[62:65], v121, s[42:43]
	v_add_u32_e32 v121, 0x3c0000, v119
	global_load_dwordx4 v[66:69], v121, s[36:37]
	global_load_dwordx4 v[70:73], v121, s[38:39]
	global_load_dwordx4 v[74:77], v121, s[40:41]
	global_load_dwordx4 v[78:81], v121, s[42:43]
	v_add_u32_e32 v121, 0x420000, v119
	global_load_dwordx4 v[82:85], v121, s[36:37]
	global_load_dwordx4 v[86:89], v121, s[38:39]
	global_load_dwordx4 v[90:93], v121, s[40:41]
	global_load_dwordx4 v[94:97], v121, s[42:43]
	v_add_u32_e32 v121, 0x480000, v119
	global_load_dwordx4 v[98:101], v121, s[36:37]
	global_load_dwordx4 v[102:105], v121, s[38:39]
	global_load_dwordx4 v[106:109], v121, s[40:41]
	global_load_dwordx4 v[110:113], v121, s[42:43]
	v_add_u32_e32 v121, 0x4e0000, v119
	global_load_dwordx4 v[192:195], v121, s[36:37]
	global_load_dwordx4 v[196:199], v121, s[38:39]
	global_load_dwordx4 v[200:203], v121, s[40:41]
	global_load_dwordx4 v[204:207], v121, s[42:43]
	v_add_u32_e32 v121, 0x540000, v119
	global_load_dwordx4 v[208:211], v121, s[36:37]
	global_load_dwordx4 v[212:215], v121, s[38:39]
	global_load_dwordx4 v[216:219], v121, s[40:41]
	global_load_dwordx4 v[220:223], v121, s[42:43]
	v_add_u32_e32 v121, 0x5a0000, v119
	global_load_dwordx4 v[224:227], v121, s[36:37]
	global_load_dwordx4 v[228:231], v121, s[38:39]
	global_load_dwordx4 v[232:235], v121, s[40:41]
	global_load_dwordx4 v[236:239], v121, s[42:43]
	s_waitcnt vmcnt(28)
	v_pk_add_f32 v[36:37], v[36:37], v[40:41]
	v_pk_add_f32 v[34:35], v[34:35], v[38:39]
	v_pk_add_f32 v[38:39], v[44:45], v[48:49]
	v_pk_add_f32 v[40:41], v[42:43], v[46:47]
	v_pk_add_f32 v[36:37], v[36:37], v[38:39]
	v_pk_add_f32 v[34:35], v[34:35], v[40:41]
	v_pk_add_f32 v[36:37], v[116:117], v[36:37]
	v_pk_add_f32 v[34:35], v[114:115], v[34:35]
	v_add_u32_e32 v121, 0x900000, v120
	global_store_dwordx4 v121, v[34:37], s[44:45]
	s_waitcnt vmcnt(25)
	v_pk_add_f32 v[52:53], v[52:53], v[56:57]
	v_pk_add_f32 v[50:51], v[50:51], v[54:55]
	v_pk_add_f32 v[54:55], v[60:61], v[64:65]
	v_pk_add_f32 v[56:57], v[58:59], v[62:63]
	v_pk_add_f32 v[52:53], v[52:53], v[54:55]
	v_pk_add_f32 v[50:51], v[50:51], v[56:57]
	v_pk_add_f32 v[52:53], v[116:117], v[52:53]
	v_pk_add_f32 v[50:51], v[114:115], v[50:51]
	v_add_u32_e32 v121, 0xa20000, v120
	global_store_dwordx4 v121, v[50:53], s[44:45]
	s_waitcnt vmcnt(22)
	v_pk_add_f32 v[68:69], v[68:69], v[72:73]
	v_pk_add_f32 v[66:67], v[66:67], v[70:71]
	v_pk_add_f32 v[70:71], v[76:77], v[80:81]
	v_pk_add_f32 v[72:73], v[74:75], v[78:79]
	v_pk_add_f32 v[68:69], v[68:69], v[70:71]
	v_pk_add_f32 v[66:67], v[66:67], v[72:73]
	v_pk_add_f32 v[68:69], v[116:117], v[68:69]
	v_pk_add_f32 v[66:67], v[114:115], v[66:67]
	v_add_u32_e32 v121, 0xb40000, v120
	global_store_dwordx4 v121, v[66:69], s[44:45]
	s_waitcnt vmcnt(19)
	v_pk_add_f32 v[84:85], v[84:85], v[88:89]
	v_pk_add_f32 v[82:83], v[82:83], v[86:87]
	v_pk_add_f32 v[86:87], v[92:93], v[96:97]
	v_pk_add_f32 v[88:89], v[90:91], v[94:95]
	v_pk_add_f32 v[84:85], v[84:85], v[86:87]
	v_pk_add_f32 v[82:83], v[82:83], v[88:89]
	v_pk_add_f32 v[84:85], v[116:117], v[84:85]
	v_pk_add_f32 v[82:83], v[114:115], v[82:83]
	v_add_u32_e32 v121, 0xc60000, v120
	global_store_dwordx4 v121, v[82:85], s[44:45]
	s_waitcnt vmcnt(16)
	v_pk_add_f32 v[100:101], v[100:101], v[104:105]
	v_pk_add_f32 v[98:99], v[98:99], v[102:103]
	v_pk_add_f32 v[102:103], v[108:109], v[112:113]
	v_pk_add_f32 v[104:105], v[106:107], v[110:111]
	v_pk_add_f32 v[100:101], v[100:101], v[102:103]
	v_pk_add_f32 v[98:99], v[98:99], v[104:105]
	v_pk_add_f32 v[100:101], v[116:117], v[100:101]
	v_pk_add_f32 v[98:99], v[114:115], v[98:99]
	v_add_u32_e32 v121, 0xd80000, v120
	global_store_dwordx4 v121, v[98:101], s[44:45]
	s_waitcnt vmcnt(13)
	v_pk_add_f32 v[194:195], v[194:195], v[198:199]
	v_pk_add_f32 v[192:193], v[192:193], v[196:197]
	v_pk_add_f32 v[196:197], v[202:203], v[206:207]
	v_pk_add_f32 v[198:199], v[200:201], v[204:205]
	v_pk_add_f32 v[194:195], v[194:195], v[196:197]
	v_pk_add_f32 v[192:193], v[192:193], v[198:199]
	v_pk_add_f32 v[194:195], v[116:117], v[194:195]
	v_pk_add_f32 v[192:193], v[114:115], v[192:193]
	v_add_u32_e32 v121, 0xea0000, v120
	global_store_dwordx4 v121, v[192:195], s[44:45]
	s_waitcnt vmcnt(10)
	v_pk_add_f32 v[210:211], v[210:211], v[214:215]
	v_pk_add_f32 v[208:209], v[208:209], v[212:213]
	v_pk_add_f32 v[212:213], v[218:219], v[222:223]
	v_pk_add_f32 v[214:215], v[216:217], v[220:221]
	v_pk_add_f32 v[210:211], v[210:211], v[212:213]
	v_pk_add_f32 v[208:209], v[208:209], v[214:215]
	v_pk_add_f32 v[210:211], v[116:117], v[210:211]
	v_pk_add_f32 v[208:209], v[114:115], v[208:209]
	v_add_u32_e32 v121, 0xfc0000, v120
	global_store_dwordx4 v121, v[208:211], s[44:45]
	s_waitcnt vmcnt(7)
	v_pk_add_f32 v[226:227], v[226:227], v[230:231]
	v_pk_add_f32 v[224:225], v[224:225], v[228:229]
	v_pk_add_f32 v[228:229], v[234:235], v[238:239]
	v_pk_add_f32 v[230:231], v[232:233], v[236:237]
	v_pk_add_f32 v[226:227], v[226:227], v[228:229]
	v_pk_add_f32 v[224:225], v[224:225], v[230:231]
	v_pk_add_f32 v[226:227], v[116:117], v[226:227]
	v_pk_add_f32 v[224:225], v[114:115], v[224:225]
	v_add_u32_e32 v121, 0x10e0000, v120
	global_store_dwordx4 v121, v[224:227], s[44:45]
	v_cmp_gt_u32_e32 vcc, 64, v0
	s_and_saveexec_b64 s[16:17], vcc
	s_cbranch_execz .Lfs4_skip
	v_add_u32_e32 v121, 0x600000, v119
	global_load_dwordx4 v[34:37], v121, s[36:37]
	global_load_dwordx4 v[38:41], v121, s[38:39]
	global_load_dwordx4 v[42:45], v121, s[40:41]
	global_load_dwordx4 v[46:49], v121, s[42:43]
	s_waitcnt vmcnt(0)
	v_pk_add_f32 v[36:37], v[36:37], v[40:41]
	v_pk_add_f32 v[34:35], v[34:35], v[38:39]
	v_pk_add_f32 v[38:39], v[44:45], v[48:49]
	v_pk_add_f32 v[40:41], v[42:43], v[46:47]
	v_pk_add_f32 v[36:37], v[36:37], v[38:39]
	v_pk_add_f32 v[34:35], v[34:35], v[40:41]
	v_pk_add_f32 v[36:37], v[116:117], v[36:37]
	v_pk_add_f32 v[34:35], v[114:115], v[34:35]
	v_add_u32_e32 v121, 0x1200000, v120
	global_store_dwordx4 v121, v[34:37], s[44:45]

; #define GAS __attribute__((address_space(1)))
; __device__ __forceinline__ void mod_group_finish(Frame& F, const Args& A, int chunk, int cg) {
;     ...
;     if (F.MISC[0] != 0u) {
;         const float* PART = (const float*)(A.ws + WS_PART); float* MOD = (float*)(A.ws + WS_MOD);
;         constexpr size_t PS = (size_t)(DBATCH + 1) * 12288;
; #pragma unroll 1
;         for (int i = threadIdx.x; i < (DBATCH + 1) * 64; i += NWAVES * 64) { const int r = i >> 6, c = 256 * cg + 4 * (i & 63);
;             const float* p = PART + (size_t)r * 12288 + c;
;             const f32x4 s = (*(const GAS f32x4*)p + *(const GAS f32x4*)(p + PS)) + (*(const GAS f32x4*)(p + 2 * PS) + *(const GAS f32x4*)(p + 3 * PS));
;             *(GAS f32x4*)(MOD + (size_t)r * MODW + 12288 * chunk + c) = s + *(const GAS f32x4*)(A.in[I_BADA] + 12288 * chunk + c); }
;     }
.LBB0_544:
	s_or_b64 exec, exec, s[16:17]
	v_mov_b32_e32 v2, s87
	s_waitcnt lgkmcnt(0)
	s_barrier
	ds_read_b32 v2, v2
	s_waitcnt lgkmcnt(0)
	v_cmp_eq_u32_e32 vcc, 0, v2
	s_cbranch_vccnz .LBB0_531
	s_add_u32 s36, s30, 0x63700000
	s_addc_u32 s37, s31, 0
	s_add_u32 s38, s36, 0x60c000
	s_addc_u32 s39, s37, 0
	s_add_u32 s40, s38, 0x60c000
	s_addc_u32 s41, s39, 0
	s_add_u32 s42, s40, 0x60c000
	s_addc_u32 s43, s41, 0
	s_add_u32 s44, s30, 0x38f18000
	s_addc_u32 s45, s31, 0
	v_lshrrev_b32_e32 v11, 6, v0
	v_or_b32_e32 v118, s14, v161
	v_lshlrev_b32_e32 v118, 2, v118
	v_mul_u32_u24_e32 v119, 0xc000, v11
	v_add_u32_e32 v119, v119, v118
	v_mul_u32_u24_e32 v120, 0x24000, v11
	v_add_u32_e32 v120, v120, v118
	global_load_dwordx4 v[114:117], v118, s[8:9]
	v_mov_b32_e32 v121, v119
	global_load_dwordx4 v[34:37], v121, s[36:37]
	global_load_dwordx4 v[38:41], v121, s[38:39]
	global_load_dwordx4 v[42:45], v121, s[40:41]
	global_load_dwordx4 v[46:49], v121, s[42:43]
	v_add_u32_e32 v121, 0x60000, v119
	global_load_dwordx4 v[50:53], v121, s[36:37]
	global_load_dwordx4 v[54:57], v121, s[38:39]
	global_load_dwordx4 v[58:61], v121, s[40:41]
	global_load_dwordx4 v[62:65], v121, s[42:43]
	v_add_u32_e32 v121, 0xc0000, v119
	global_load_dwordx4 v[66:69], v121, s[36:37]
	global_load_dwordx4 v[70:73], v121, s[38:39]
	global_load_dwordx4 v[74:77], v121, s[40:41]
	global_load_dwordx4 v[78:81], v121, s[42:43]
	v_add_u32_e32 v121, 0x120000, v119
	global_load_dwordx4 v[82:85], v121, s[36:37]
	global_load_dwordx4 v[86:89], v121, s[38:39]
	global_load_dwordx4 v[90:93], v121, s[40:41]
	global_load_dwordx4 v[94:97], v121, s[42:43]
	v_add_u32_e32 v121, 0x180000, v119
	global_load_dwordx4 v[98:101], v121, s[36:37]
	global_load_dwordx4 v[102:105], v121, s[38:39]
	global_load_dwordx4 v[106:109], v121, s[40:41]
	global_load_dwordx4 v[110:113], v121, s[42:43]
	v_add_u32_e32 v121, 0x1e0000, v119
	global_load_dwordx4 v[192:195], v121, s[36:37]
	global_load_dwordx4 v[196:199], v121, s[38:39]
	global_load_dwordx4 v[200:203], v121, s[40:41]
	global_load_dwordx4 v[204:207], v121, s[42:43]
	v_add_u32_e32 v121, 0x240000, v119
	global_load_dwordx4 v[208:211], v121, s[36:37]
	global_load_dwordx4 v[212:215], v121, s[38:39]
	global_load_dwordx4 v[216:219], v121, s[40:41]
	global_load_dwordx4 v[220:223], v121, s[42:43]
	v_add_u32_e32 v121, 0x2a0000, v119
	global_load_dwordx4 v[224:227], v121, s[36:37]
	global_load_dwordx4 v[228:231], v121, s[38:39]
	global_load_dwordx4 v[232:235], v121, s[40:41]
	global_load_dwordx4 v[236:239], v121, s[42:43]
	s_waitcnt vmcnt(28)
	v_pk_add_f32 v[36:37], v[36:37], v[40:41]
	v_pk_add_f32 v[34:35], v[34:35], v[38:39]
	v_pk_add_f32 v[38:39], v[44:45], v[48:49]
	v_pk_add_f32 v[40:41], v[42:43], v[46:47]
	v_pk_add_f32 v[36:37], v[36:37], v[38:39]
	v_pk_add_f32 v[34:35], v[34:35], v[40:41]
	v_pk_add_f32 v[36:37], v[116:117], v[36:37]
	v_pk_add_f32 v[34:35], v[114:115], v[34:35]
	v_mov_b32_e32 v121, v120
	global_store_dwordx4 v121, v[34:37], s[44:45]
	s_waitcnt vmcnt(25)
	v_pk_add_f32 v[52:53], v[52:53], v[56:57]
	v_pk_add_f32 v[50:51], v[50:51], v[54:55]
	v_pk_add_f32 v[54:55], v[60:61], v[64:65]
	v_pk_add_f32 v[56:57], v[58:59], v[62:63]
	v_pk_add_f32 v[52:53], v[52:53], v[54:55]
	v_pk_add_f32 v[50:51], v[50:51], v[56:57]
	v_pk_add_f32 v[52:53], v[116:117], v[52:53]
	v_pk_add_f32 v[50:51], v[114:115], v[50:51]
	v_add_u32_e32 v121, 0x120000, v120
	global_store_dwordx4 v121, v[50:53], s[44:45]
	s_waitcnt vmcnt(22)
	v_pk_add_f32 v[68:69], v[68:69], v[72:73]
	v_pk_add_f32 v[66:67], v[66:67], v[70:71]
	v_pk_add_f32 v[70:71], v[76:77], v[80:81]
	v_pk_add_f32 v[72:73], v[74:75], v[78:79]
	v_pk_add_f32 v[68:69], v[68:69], v[70:71]
	v_pk_add_f32 v[66:67], v[66:67], v[72:73]
	v_pk_add_f32 v[68:69], v[116:117], v[68:69]
	v_pk_add_f32 v[66:67], v[114:115], v[66:67]
	v_add_u32_e32 v121, 0x240000, v120
	global_store_dwordx4 v121, v[66:69], s[44:45]
	s_waitcnt vmcnt(19)
	v_pk_add_f32 v[84:85], v[84:85], v[88:89]
	v_pk_add_f32 v[82:83], v[82:83], v[86:87]
	v_pk_add_f32 v[86:87], v[92:93], v[96:97]
	v_pk_add_f32 v[88:89], v[90:91], v[94:95]
	v_pk_add_f32 v[84:85], v[84:85], v[86:87]
	v_pk_add_f32 v[82:83], v[82:83], v[88:89]
	v_pk_add_f32 v[84:85], v[116:117], v[84:85]
	v_pk_add_f32 v[82:83], v[114:115], v[82:83]
	v_add_u32_e32 v121, 0x360000, v120
	global_store_dwordx4 v121, v[82:85], s[44:45]
	s_waitcnt vmcnt(16)
	v_pk_add_f32 v[100:101], v[100:101], v[104:105]
	v_pk_add_f32 v[98:99], v[98:99], v[102:103]
	v_pk_add_f32 v[102:103], v[108:109], v[112:113]
	v_pk_add_f32 v[104:105], v[106:107], v[110:111]
	v_pk_add_f32 v[100:101], v[100:101], v[102:103]
	v_pk_add_f32 v[98:99], v[98:99], v[104:105]
	v_pk_add_f32 v[100:101], v[116:117], v[100:101]
	v_pk_add_f32 v[98:99], v[114:115], v[98:99]
	v_add_u32_e32 v121, 0x480000, v120
	global_store_dwordx4 v121, v[98:101], s[44:45]
	s_waitcnt vmcnt(13)
	v_pk_add_f32 v[194:195], v[194:195], v[198:199]
	v_pk_add_f32 v[192:193], v[192:193], v[196:197]
	v_pk_add_f32 v[196:197], v[202:203], v[206:207]
	v_pk_add_f32 v[198:199], v[200:201], v[204:205]
	v_pk_add_f32 v[194:195], v[194:195], v[196:197]
	v_pk_add_f32 v[192:193], v[192:193], v[198:199]
	v_pk_add_f32 v[194:195], v[116:117], v[194:195]
	v_pk_add_f32 v[192:193], v[114:115], v[192:193]
	v_add_u32_e32 v121, 0x5a0000, v120
	global_store_dwordx4 v121, v[192:195], s[44:45]
	s_waitcnt vmcnt(10)
	v_pk_add_f32 v[210:211], v[210:211], v[214:215]
	v_pk_add_f32 v[208:209], v[208:209], v[212:213]
	v_pk_add_f32 v[212:213], v[218:219], v[222:223]
	v_pk_add_f32 v[214:215], v[216:217], v[220:221]
	v_pk_add_f32 v[210:211], v[210:211], v[212:213]
	v_pk_add_f32 v[208:209], v[208:209], v[214:215]
	v_pk_add_f32 v[210:211], v[116:117], v[210:211]
	v_pk_add_f32 v[208:209], v[114:115], v[208:209]
	v_add_u32_e32 v121, 0x6c0000, v120
	global_store_dwordx4 v121, v[208:211], s[44:45]
	s_waitcnt vmcnt(7)
; #define GAS __attribute__((address_space(1)))
; __device__ __forceinline__ void mod_group_finish(Frame& F, const Args& A, int chunk, int cg) {
;     ...
;     if (F.MISC[0] != 0u) {
;         const float* PART = (const float*)(A.ws + WS_PART); float* MOD = (float*)(A.ws + WS_MOD);
;         constexpr size_t PS = (size_t)(DBATCH + 1) * 12288;
; #pragma unroll 1
;         for (int i = threadIdx.x; i < (DBATCH + 1) * 64; i += NWAVES * 64) { const int r = i >> 6, c = 256 * cg + 4 * (i & 63);
;             const float* p = PART + (size_t)r * 12288 + c;
;             const f32x4 s = (*(const GAS f32x4*)p + *(const GAS f32x4*)(p + PS)) + (*(const GAS f32x4*)(p + 2 * PS) + *(const GAS f32x4*)(p + 3 * PS));
;             *(GAS f32x4*)(MOD + (size_t)r * MODW + 12288 * chunk + c) = s + *(const GAS f32x4*)(A.in[I_BADA] + 12288 * chunk + c); }
;     }
	v_pk_add_f32 v[226:227], v[226:227], v[230:231]
	v_pk_add_f32 v[224:225], v[224:225], v[228:229]
	v_pk_add_f32 v[228:229], v[234:235], v[238:239]
	v_pk_add_f32 v[230:231], v[232:233], v[236:237]
	v_pk_add_f32 v[226:227], v[226:227], v[228:229]
	v_pk_add_f32 v[224:225], v[224:225], v[230:231]
	v_pk_add_f32 v[226:227], v[116:117], v[226:227]
	v_pk_add_f32 v[224:225], v[114:115], v[224:225]
	v_add_u32_e32 v121, 0x7e0000, v120
	global_store_dwordx4 v121, v[224:227], s[44:45]
	v_add_u32_e32 v121, 0x300000, v119
	global_load_dwordx4 v[34:37], v121, s[36:37]
	global_load_dwordx4 v[38:41], v121, s[38:39]
	global_load_dwordx4 v[42:45], v121, s[40:41]
	global_load_dwordx4 v[46:49], v121, s[42:43]
	v_add_u32_e32 v121, 0x360000, v119
	global_load_dwordx4 v[50:53], v121, s[36:37]
	global_load_dwordx4 v[54:57], v121, s[38:39]
	global_load_dwordx4 v[58:61], v121, s[40:41]
	global_load_dwordx4 v[62:65], v121, s[42:43]
	v_add_u32_e32 v121, 0x3c0000, v119
	global_load_dwordx4 v[66:69], v121, s[36:37]
	global_load_dwordx4 v[70:73], v121, s[38:39]
	global_load_dwordx4 v[74:77], v121, s[40:41]
	global_load_dwordx4 v[78:81], v121, s[42:43]
	v_add_u32_e32 v121, 0x420000, v119
	global_load_dwordx4 v[82:85], v121, s[36:37]
	global_load_dwordx4 v[86:89], v121, s[38:39]
	global_load_dwordx4 v[90:93], v121, s[40:41]
	global_load_dwordx4 v[94:97], v121, s[42:43]
	v_add_u32_e32 v121, 0x480000, v119
	global_load_dwordx4 v[98:101], v121, s[36:37]
	global_load_dwordx4 v[102:105], v121, s[38:39]
	global_load_dwordx4 v[106:109], v121, s[40:41]
	global_load_dwordx4 v[110:113], v121, s[42:43]
	v_add_u32_e32 v121, 0x4e0000, v119
	global_load_dwordx4 v[192:195], v121, s[36:37]
	global_load_dwordx4 v[196:199], v121, s[38:39]
	global_load_dwordx4 v[200:203], v121, s[40:41]
	global_load_dwordx4 v[204:207], v121, s[42:43]
	v_add_u32_e32 v121, 0x540000, v119
	global_load_dwordx4 v[208:211], v121, s[36:37]
	global_load_dwordx4 v[212:215], v121, s[38:39]
	global_load_dwordx4 v[216:219], v121, s[40:41]
	global_load_dwordx4 v[220:223], v121, s[42:43]
	v_add_u32_e32 v121, 0x5a0000, v119
	global_load_dwordx4 v[224:227], v121, s[36:37]
	global_load_dwordx4 v[228:231], v121, s[38:39]
	global_load_dwordx4 v[232:235], v121, s[40:41]
	global_load_dwordx4 v[236:239], v121, s[42:43]
	s_waitcnt vmcnt(28)
	v_pk_add_f32 v[36:37], v[36:37], v[40:41]
	v_pk_add_f32 v[34:35], v[34:35], v[38:39]
	v_pk_add_f32 v[38:39], v[44:45], v[48:49]
	v_pk_add_f32 v[40:41], v[42:43], v[46:47]
	v_pk_add_f32 v[36:37], v[36:37], v[38:39]
	v_pk_add_f32 v[34:35], v[34:35], v[40:41]
	v_pk_add_f32 v[36:37], v[116:117], v[36:37]
	v_pk_add_f32 v[34:35], v[114:115], v[34:35]
	v_add_u32_e32 v121, 0x900000, v120
	global_store_dwordx4 v121, v[34:37], s[44:45]
	s_waitcnt vmcnt(25)
	v_pk_add_f32 v[52:53], v[52:53], v[56:57]
	v_pk_add_f32 v[50:51], v[50:51], v[54:55]
	v_pk_add_f32 v[54:55], v[60:61], v[64:65]
	v_pk_add_f32 v[56:57], v[58:59], v[62:63]
	v_pk_add_f32 v[52:53], v[52:53], v[54:55]
	v_pk_add_f32 v[50:51], v[50:51], v[56:57]
	v_pk_add_f32 v[52:53], v[116:117], v[52:53]
	v_pk_add_f32 v[50:51], v[114:115], v[50:51]
	v_add_u32_e32 v121, 0xa20000, v120
	global_store_dwordx4 v121, v[50:53], s[44:45]
	s_waitcnt vmcnt(22)
	v_pk_add_f32 v[68:69], v[68:69], v[72:73]
	v_pk_add_f32 v[66:67], v[66:67], v[70:71]
	v_pk_add_f32 v[70:71], v[76:77], v[80:81]
	v_pk_add_f32 v[72:73], v[74:75], v[78:79]
	v_pk_add_f32 v[68:69], v[68:69], v[70:71]
	v_pk_add_f32 v[66:67], v[66:67], v[72:73]
	v_pk_add_f32 v[68:69], v[116:117], v[68:69]
	v_pk_add_f32 v[66:67], v[114:115], v[66:67]
	v_add_u32_e32 v121, 0xb40000, v120
	global_store_dwordx4 v121, v[66:69], s[44:45]
	s_waitcnt vmcnt(19)
	v_pk_add_f32 v[84:85], v[84:85], v[88:89]
	v_pk_add_f32 v[82:83], v[82:83], v[86:87]
	v_pk_add_f32 v[86:87], v[92:93], v[96:97]
	v_pk_add_f32 v[88:89], v[90:91], v[94:95]
	v_pk_add_f32 v[84:85], v[84:85], v[86:87]
	v_pk_add_f32 v[82:83], v[82:83], v[88:89]
	v_pk_add_f32 v[84:85], v[116:117], v[84:85]
	v_pk_add_f32 v[82:83], v[114:115], v[82:83]
	v_add_u32_e32 v121, 0xc60000, v120
	global_store_dwordx4 v121, v[82:85], s[44:45]
	s_waitcnt vmcnt(16)
	v_pk_add_f32 v[100:101], v[100:101], v[104:105]
	v_pk_add_f32 v[98:99], v[98:99], v[102:103]
	v_pk_add_f32 v[102:103], v[108:109], v[112:113]
	v_pk_add_f32 v[104:105], v[106:107], v[110:111]
	v_pk_add_f32 v[100:101], v[100:101], v[102:103]
	v_pk_add_f32 v[98:99], v[98:99], v[104:105]
	v_pk_add_f32 v[100:101], v[116:117], v[100:101]
	v_pk_add_f32 v[98:99], v[114:115], v[98:99]
	v_add_u32_e32 v121, 0xd80000, v120
	global_store_dwordx4 v121, v[98:101], s[44:45]
	s_waitcnt vmcnt(13)
	v_pk_add_f32 v[194:195], v[194:195], v[198:199]
	v_pk_add_f32 v[192:193], v[192:193], v[196:197]
	v_pk_add_f32 v[196:197], v[202:203], v[206:207]
	v_pk_add_f32 v[198:199], v[200:201], v[204:205]
	v_pk_add_f32 v[194:195], v[194:195], v[196:197]
	v_pk_add_f32 v[192:193], v[192:193], v[198:199]
	v_pk_add_f32 v[194:195], v[116:117], v[194:195]
	v_pk_add_f32 v[192:193], v[114:115], v[192:193]
	v_add_u32_e32 v121, 0xea0000, v120
	global_store_dwordx4 v121, v[192:195], s[44:45]
	s_waitcnt vmcnt(10)
	v_pk_add_f32 v[210:211], v[210:211], v[214:215]
	v_pk_add_f32 v[208:209], v[208:209], v[212:213]
	v_pk_add_f32 v[212:213], v[218:219], v[222:223]
	v_pk_add_f32 v[214:215], v[216:217], v[220:221]
	v_pk_add_f32 v[210:211], v[210:211], v[212:213]
	v_pk_add_f32 v[208:209], v[208:209], v[214:215]
	v_pk_add_f32 v[210:211], v[116:117], v[210:211]
	v_pk_add_f32 v[208:209], v[114:115], v[208:209]
	v_add_u32_e32 v121, 0xfc0000, v120
	global_store_dwordx4 v121, v[208:211], s[44:45]
	s_waitcnt vmcnt(7)
	v_pk_add_f32 v[226:227], v[226:227], v[230:231]
	v_pk_add_f32 v[224:225], v[224:225], v[228:229]
	v_pk_add_f32 v[228:229], v[234:235], v[238:239]
	v_pk_add_f32 v[230:231], v[232:233], v[236:237]
	v_pk_add_f32 v[226:227], v[226:227], v[228:229]
	v_pk_add_f32 v[224:225], v[224:225], v[230:231]
	v_pk_add_f32 v[226:227], v[116:117], v[226:227]
	v_pk_add_f32 v[224:225], v[114:115], v[224:225]
	v_add_u32_e32 v121, 0x10e0000, v120
	global_store_dwordx4 v121, v[224:227], s[44:45]
	v_cmp_gt_u32_e32 vcc, 64, v0
	s_and_saveexec_b64 s[26:27], vcc
	s_cbranch_execz .Lfs6_skip
	v_add_u32_e32 v121, 0x600000, v119
	global_load_dwordx4 v[34:37], v121, s[36:37]
	global_load_dwordx4 v[38:41], v121, s[38:39]
	global_load_dwordx4 v[42:45], v121, s[40:41]
	global_load_dwordx4 v[46:49], v121, s[42:43]
	s_waitcnt vmcnt(0)
	v_pk_add_f32 v[36:37], v[36:37], v[40:41]
	v_pk_add_f32 v[34:35], v[34:35], v[38:39]
	v_pk_add_f32 v[38:39], v[44:45], v[48:49]
	v_pk_add_f32 v[40:41], v[42:43], v[46:47]
	v_pk_add_f32 v[36:37], v[36:37], v[38:39]
	v_pk_add_f32 v[34:35], v[34:35], v[40:41]
	v_pk_add_f32 v[36:37], v[116:117], v[36:37]
	v_pk_add_f32 v[34:35], v[114:115], v[34:35]
	v_add_u32_e32 v121, 0x1200000, v120
	global_store_dwordx4 v121, v[34:37], s[44:45]
.Lfs6_skip:
	s_or_b64 exec, exec, s[26:27]
	s_branch .LBB0_531
